# spatial-gating MFMA chain: counted wait vmcnt(1) before the first MFMA (needs only the first weight fragment; the second fragment's load is always younger)
# baseline (speedup 1.0000x reference)
; #define LAS __attribute__((address_space(3)))
; __device__ __forceinline__ void sgu_unit(LAS unsigned char* lds, const bf16_t* proj, bf16_t* Y, const bf16_t* wsb  , const float* lnw, const float* lnb, const float* bs  , int row0, unsigned long long* gss, const int wave_s) {
;     ...
;         const bf16_t* wrow = wg + (size_t)(32 * tt + r32) * 128 + 8 * hi;
;         const int nk = 2 * (tt + 1);
;         bf16x8 wf[8];
; #pragma unroll
;         for (int k = 0; k < 8; ++k) if (k < nk) wf[k] = *(g_bf16x8*)(wrow + 16 * k);
; #pragma unroll
;         for (int k = 0; k < 8; ++k) if (k < nk) {
;             const bf16x8 a = *(const LAS bf16x8*)(ab + k * 32);
;             acc = __builtin_amdgcn_mfma_f32_32x32x16_bf16(a, wf[k], acc, 0, 0, 0);
.LBB0_849:
	ds_read_b128 v[22:25], v17
	ds_read_b128 v[60:63], v17 offset:32
	s_and_b64 vcc, exec, s[8:9]
	s_waitcnt vmcnt(1) lgkmcnt(0)
	v_mfma_f32_32x32x16_bf16 v[18:33], v[22:25], v[18:21], 0
	s_waitcnt vmcnt(0) lgkmcnt(0)
	v_mfma_f32_32x32x16_bf16 v[18:33], v[60:63], v[46:49], v[18:33]
	s_cbranch_vccnz .LBB0_851
	ds_read_b128 v[46:49], v17 offset:64
	s_waitcnt lgkmcnt(0)
	v_mfma_f32_32x32x16_bf16 v[18:33], v[46:49], v[42:45], v[18:33]
